# ret_out tile fill: all 20 global loads (v, k, cross-chunk state) issued up front into free VGPRs with counted waits, replacing 8 serial load-wait round trips
# baseline (speedup 1.0000x reference)
.LBB0_1083:
	s_and_b32 s10, s6, 3
	v_cvt_f32_ubyte0_e32 v0, s10
	v_sub_f32_e32 v0, 0xc0a00000, v0
	s_mov_b32 s0, 0xc2fc0000
	v_cmp_gt_f32_e32 vcc, s0, v0
	s_lshl_b32 s7, s6, 5
	s_and_b32 s43, s7, 0xffffff80
	v_cndmask_b32_e32 v2, 0, v248, vcc
	v_add_f32_e32 v0, v0, v2
	v_exp_f32_e32 v0, v0
	s_and_b64 s[0:1], vcc, exec
	s_cselect_b32 s0, 0xffffffc0, 0
	v_mov_b32_e32 v7, v194
	v_ldexp_f32 v0, v0, s0
	v_readlane_b32 s44, v251, 54
	v_sub_f32_e32 v19, 1.0, v0
	v_lshrrev_b32_e32 v18, 1, v7
	v_mov_b32_e32 v0, s7
	s_movk_i32 s0, 0x7f
	v_readlane_b32 s50, v251, 60
	v_readlane_b32 s51, v251, 61
	v_bfi_b32 v0, s0, v18, v0
	v_and_b32_e32 v28, 1, v7
	v_mov_b64_e32 v[2:3], s[50:51]
	v_mad_i64_i32 v[4:5], s[0:1], v0, s3, v[2:3]
	s_lshl_b32 s88, s10, 8
	v_lshl_add_u64 v[8:9], v[4:5], 0, s[88:89]
	v_lshlrev_b32_e32 v2, 7, v28
	v_mov_b32_e32 v3, v1
	v_lshl_add_u64 v[16:17], v[8:9], 0, v[2:3]
	global_load_dwordx4 v[8:11], v[16:17], off offset:3120
	global_load_dwordx4 v[12:15], v[16:17], off offset:3104
	global_load_dwordx4 v[20:23], v[16:17], off offset:3088
	global_load_dwordx4 v[24:27], v[16:17], off offset:3072
	global_load_dwordx4 v[140:143], v[16:17], off offset:3184
	global_load_dwordx4 v[144:147], v[16:17], off offset:3168
	global_load_dwordx4 v[148:151], v[16:17], off offset:3152
	global_load_dwordx4 v[152:155], v[16:17], off offset:3136
	v_bfe_u32 v6, v7, 1, 7
	v_lshlrev_b32_e32 v0, 6, v28
	v_mul_u32_u24_e32 v28, 0x2200, v28
	v_lshlrev_b32_e32 v28, 1, v28
	v_lshlrev_b32_e32 v29, 1, v6
	v_add3_u32 v30, s4, v28, v29
	v_add3_u32 v28, s4, v29, v28
	s_lshl_b32 s8, s10, 7
	s_mov_b32 s9, s89
	v_lshl_add_u64 v[4:5], v[4:5], 0, s[8:9]
	v_lshl_add_u64 v[4:5], v[4:5], 0, v[0:1]
	global_load_dwordx4 v[156:159], v[4:5], off offset:2560
	global_load_dwordx4 v[160:163], v[4:5], off offset:2576
	global_load_dwordx4 v[164:167], v[4:5], off offset:2592
	global_load_dwordx4 v[168:171], v[4:5], off offset:2608
	s_ashr_i32 s7, s6, 31
	s_lshl_b32 s11, s10, 6
	s_lshl_b64 s[0:1], s[6:7], 15
	s_add_u32 s0, s24, s0
	s_addc_u32 s1, s25, s1
	v_lshlrev_b32_e32 v212, 8, v6
	v_mov_b32_e32 v213, v1
	v_lshl_add_u64 v[214:215], s[0:1], 0, v[212:213]
	v_lshl_add_u64 v[214:215], v[214:215], 0, v[2:3]
	global_load_dwordx4 v[172:175], v[214:215], off offset:48
	global_load_dwordx4 v[176:179], v[214:215], off offset:32
	global_load_dwordx4 v[180:183], v[214:215], off offset:16
	global_load_dwordx4 v[184:187], v[214:215], off
	global_load_dwordx4 v[196:199], v[214:215], off offset:112
	global_load_dwordx4 v[200:203], v[214:215], off offset:96
	global_load_dwordx4 v[204:207], v[214:215], off offset:80
	global_load_dwordx4 v[208:211], v[214:215], off offset:64
	v_and_b32_e32 v66, 15, v7
	v_cmp_gt_f32_e32 vcc, s69, v19
	v_mul_u32_u24_e32 v67, 0x90, v66
	v_and_b32_e32 v122, 0x60, v18
	v_mul_u32_u24_e32 v69, 0x110, v66
	s_mov_b32 s2, 0
	v_or_b32_e32 v125, v122, v66
	v_readlane_b32 s45, v251, 55
	v_readlane_b32 s46, v251, 56
	v_readlane_b32 s47, v251, 57
	v_readlane_b32 s48, v251, 58
	v_readlane_b32 s49, v251, 59
	v_readlane_b32 s52, v251, 62
	v_readlane_b32 s53, v251, 63
	v_readlane_b32 s54, v252, 0
	v_readlane_b32 s55, v252, 1
	v_readlane_b32 s56, v252, 2
	v_readlane_b32 s57, v252, 3
	v_readlane_b32 s58, v252, 4
	v_readlane_b32 s59, v252, 5
	s_waitcnt vmcnt(16)
	ds_write_b16 v30, v24
	ds_write_b16_d16_hi v28, v24 offset:272
	ds_write_b16 v30, v25 offset:544
	ds_write_b16_d16_hi v28, v25 offset:816
	ds_write_b16 v30, v26 offset:1088
	ds_write_b16_d16_hi v28, v26 offset:1360
	ds_write_b16 v30, v27 offset:1632
	ds_write_b16_d16_hi v28, v27 offset:1904
	ds_write_b16 v30, v20 offset:2176
	ds_write_b16_d16_hi v28, v20 offset:2448
	ds_write_b16 v30, v21 offset:2720
	ds_write_b16_d16_hi v28, v21 offset:2992
	ds_write_b16 v30, v22 offset:3264
	ds_write_b16_d16_hi v28, v22 offset:3536
	ds_write_b16 v30, v23 offset:3808
	ds_write_b16_d16_hi v28, v23 offset:4080
	ds_write_b16 v30, v12 offset:4352
	ds_write_b16_d16_hi v28, v12 offset:4624
	ds_write_b16 v30, v13 offset:4896
	ds_write_b16_d16_hi v28, v13 offset:5168
	ds_write_b16 v30, v14 offset:5440
	ds_write_b16_d16_hi v28, v14 offset:5712
	ds_write_b16 v30, v15 offset:5984
	ds_write_b16_d16_hi v28, v15 offset:6256
	ds_write_b16 v30, v8 offset:6528
	ds_write_b16_d16_hi v28, v8 offset:6800
	ds_write_b16 v30, v9 offset:7072
	ds_write_b16_d16_hi v28, v9 offset:7344
	ds_write_b16 v30, v10 offset:7616
	ds_write_b16_d16_hi v28, v10 offset:7888
	ds_write_b16 v30, v11 offset:8160
	ds_write_b16_d16_hi v28, v11 offset:8432
	s_waitcnt vmcnt(12)
	ds_write_b16 v30, v152 offset:8704
	ds_write_b16_d16_hi v28, v152 offset:8976
	ds_write_b16 v30, v153 offset:9248
	ds_write_b16_d16_hi v28, v153 offset:9520
	ds_write_b16 v30, v154 offset:9792
	ds_write_b16_d16_hi v28, v154 offset:10064
	ds_write_b16 v30, v155 offset:10336
	ds_write_b16_d16_hi v28, v155 offset:10608
	ds_write_b16 v30, v148 offset:10880
	ds_write_b16_d16_hi v28, v148 offset:11152
	ds_write_b16 v30, v149 offset:11424
	ds_write_b16_d16_hi v28, v149 offset:11696
	ds_write_b16 v30, v150 offset:11968
	ds_write_b16_d16_hi v28, v150 offset:12240
	ds_write_b16 v30, v151 offset:12512
	ds_write_b16_d16_hi v28, v151 offset:12784
	ds_write_b16 v30, v144 offset:13056
	ds_write_b16_d16_hi v28, v144 offset:13328
	ds_write_b16 v30, v145 offset:13600
	ds_write_b16_d16_hi v28, v145 offset:13872
	ds_write_b16 v30, v146 offset:14144
	ds_write_b16_d16_hi v28, v146 offset:14416
	ds_write_b16 v30, v147 offset:14688
	ds_write_b16_d16_hi v28, v147 offset:14960
	ds_write_b16 v30, v140 offset:15232
	ds_write_b16_d16_hi v28, v140 offset:15504
	ds_write_b16 v30, v141 offset:15776
	ds_write_b16_d16_hi v28, v141 offset:16048
	ds_write_b16 v30, v142 offset:16320
	ds_write_b16_d16_hi v28, v142 offset:16592
	ds_write_b16 v30, v143 offset:16864
	ds_write_b16_d16_hi v28, v143 offset:17136
	v_mul_u32_u24_e32 v8, 0x48, v6
	v_lshlrev_b32_e32 v8, 1, v8
	v_add3_u32 v21, s4, v8, v0
	v_lshlrev_b32_e32 v0, 8, v6
	v_bfe_u32 v20, v7, 4, 2
	v_lshlrev_b32_e32 v68, 3, v20
	v_lshlrev_b32_e32 v114, 2, v20
	v_add3_u32 v127, v69, v68, s4
	v_sub_u32_e32 v128, v66, v114
	s_waitcnt vmcnt(8)
	ds_write_b128 v21, v[156:159] offset:34816
	ds_write_b128 v21, v[160:163] offset:34832
	ds_write_b128 v21, v[164:167] offset:34848
	v_lshl_add_u64 v[4:5], s[0:1], 0, v[0:1]
	v_lshl_add_u64 v[22:23], v[4:5], 0, v[2:3]
	s_and_b64 s[0:1], vcc, exec
	s_cselect_b32 s0, 32, 0
	v_ldexp_f32 v0, v19, s0
	v_log_f32_e32 v0, v0
	s_mov_b32 s0, 0x3f317217
	s_lshl_b32 s7, s10, 9
	ds_write_b128 v21, v[168:171] offset:34864
	s_waitcnt vmcnt(4)
	v_mov_b32_e32 v2, v172
	v_mov_b32_e32 v3, v173
	v_mov_b32_e32 v4, v174
	v_mov_b32_e32 v5, v175
	v_mov_b32_e32 v6, v176
	v_mov_b32_e32 v7, v177
	v_mov_b32_e32 v8, v178
	v_mov_b32_e32 v9, v179
	v_mov_b32_e32 v10, v180
	v_mov_b32_e32 v11, v181
	v_mov_b32_e32 v12, v182
	v_mov_b32_e32 v13, v183
	v_mov_b32_e32 v14, v184
	v_mov_b32_e32 v15, v185
	v_mov_b32_e32 v16, v186
	v_mov_b32_e32 v17, v187
	v_cvt_pk_bf16_f32 v6, v6, v7
	v_cvt_pk_bf16_f32 v7, v8, v9
	v_cvt_pk_bf16_f32 v14, v14, v15
	v_cvt_pk_bf16_f32 v15, v16, v17
	v_cvt_pk_bf16_f32 v16, v10, v11
	v_cvt_pk_bf16_f32 v17, v12, v13
	v_cvt_pk_bf16_f32 v8, v2, v3
	v_cvt_pk_bf16_f32 v9, v4, v5
	ds_write_b128 v21, v[14:17] offset:53248
	ds_write_b128 v21, v[6:9] offset:53264
	s_waitcnt vmcnt(0)
	v_mov_b32_e32 v2, v196
	v_mov_b32_e32 v3, v197
	v_mov_b32_e32 v4, v198
	v_mov_b32_e32 v5, v199
	v_mov_b32_e32 v10, v204
	v_mov_b32_e32 v11, v205
	v_mov_b32_e32 v12, v206
	v_mov_b32_e32 v13, v207
	v_mov_b32_e32 v6, v200
	v_mov_b32_e32 v7, v201
	v_mov_b32_e32 v8, v202
	v_mov_b32_e32 v9, v203
	v_mov_b32_e32 v14, v208
	v_mov_b32_e32 v15, v209
	v_mov_b32_e32 v16, v210
	v_mov_b32_e32 v17, v211
	s_waitcnt vmcnt(2)
	v_cvt_pk_bf16_f32 v6, v6, v7
	v_cvt_pk_bf16_f32 v7, v8, v9
	v_cvt_pk_bf16_f32 v8, v2, v3
	v_mul_f32_e32 v2, 0x3f317217, v0
	v_fma_f32 v2, v0, s0, -v2
	v_fmac_f32_e32 v2, 0x3377d1cf, v0
	s_mov_b32 s0, 0x7f800000
	v_fmac_f32_e32 v2, 0x3f317217, v0
	v_cmp_lt_f32_e64 s[0:1], |v0|, s0
	s_waitcnt vmcnt(0)
	v_cvt_pk_bf16_f32 v14, v14, v15
	v_cvt_pk_bf16_f32 v15, v16, v17
	v_cndmask_b32_e64 v0, v0, v2, s[0:1]
	v_cndmask_b32_e32 v2, 0, v231, vcc
	v_cmp_lt_i32_e32 vcc, v237, v235
	v_sub_f32_e32 v115, v0, v2
	v_cvt_pk_bf16_f32 v16, v10, v11
	v_cndmask_b32_e32 v0, v234, v237, vcc
	v_cmp_lt_i32_e32 vcc, v236, v235
	v_lshlrev_b32_e32 v123, 2, v0
	v_cvt_pk_bf16_f32 v17, v12, v13
	v_cndmask_b32_e32 v0, v234, v236, vcc
	v_lshlrev_b32_e32 v124, 2, v0
	v_lshlrev_b32_e32 v0, 4, v20
	v_add3_u32 v46, s4, v0, v67
	v_cvt_pk_bf16_f32 v9, v4, v5
	v_add_u32_e32 v54, 0x900, v46
	v_add_u32_e32 v62, 0x1200, v46
	ds_write_b128 v21, v[14:17] offset:53280
	ds_write_b128 v21, v[6:9] offset:53296
	s_waitcnt lgkmcnt(0)
	s_barrier
	ds_read_b128 v[2:5], v46 offset:53248
	ds_read_b128 v[6:9], v46 offset:53312
	ds_read_b128 v[10:13], v46 offset:55552
	ds_read_b128 v[14:17], v46 offset:55616
	ds_read_b128 v[18:21], v46 offset:57856
	ds_read_b128 v[22:25], v46 offset:57920
	ds_read_b128 v[26:29], v46 offset:60160
	ds_read_b128 v[30:33], v46 offset:60224
	ds_read_b128 v[34:37], v46 offset:62464
	ds_read_b128 v[38:41], v46 offset:62528
	ds_read_b128 v[42:45], v46 offset:64768
	ds_read_b128 v[46:49], v46 offset:64832
	ds_read_b128 v[50:53], v54 offset:64768
	ds_read_b128 v[54:57], v54 offset:64832
	ds_read_b128 v[58:61], v62 offset:64768
	ds_read_b128 v[62:65], v62 offset:64832
	s_add_u32 s0, s5, s7
	s_addc_u32 s1, s20, 0
	s_add_u32 s12, s21, s7
	s_addc_u32 s13, s39, 0
	v_lshl_add_u64 v[116:117], s[0:1], 0, v[0:1]
	v_lshl_add_u64 v[118:119], s[12:13], 0, v[0:1]
	v_add3_u32 v126, v67, v0, s42
	s_mov_b64 s[0:1], -1
	s_lshl_b32 s88, s11, 1
	v_lshlrev_b32_e32 v0, 1, v68
	s_lshl_b32 s12, s8, 1
